# MLA loop: hoist next-V LDS write from tail to mid-iteration (between PV halves), K-frag LDS addresses from 2 bases + immediate offsets (-4 VALU/iter)
# speedup vs baseline: 1.0090x; 1.0008x over previous
; #define SBAR() __builtin_amdgcn_sched_barrier(0)
; #define RESC(a) do { if (__any((a) < 1.f)) { if (hi == 0) al_l[r32] = (a); asm volatile("s_waitcnt lgkmcnt(0)" ::: "memory"); \
;     _Pragma("unroll") for (int d = 0; d < 4; ++d) _Pragma("unroll") for (int r = 0; r < 16; ++r) o[d][r] *= al_l[crow(r, hi)]; } } while (0)
; template <int NVT, int VRSB, int KB, int DH, int VT> __device__ __forceinline__ void pvh_pro(int vb, s16x4 (&f)[DH + 1][2]) { if constexpr (VT < DH && VT < NVT) { pvh_ld<VT, KB, VRSB>(f[VT], vb); pvh_pro<NVT, VRSB, KB, DH, VT + 1>(vb, f); } }
; __device__ __forceinline__ void partialSM16(f32x4 (&s)[4][2], float (&m_reg)[2], float (&alpha)[2], const float C, const float thr_s) {
;     ...
;   for (int qt = 0; qt < 2; ++qt) { const float mnC = -mn[qt] * C;
; #pragma unroll
;     for (int kt = 0; kt < 4; ++kt)
; #pragma unroll
;       for (int r = 0; r < 4; ++r) s[kt][qt][r] = fmaf(s[kt][qt][r], C, mnC); }
; #pragma unroll
;   for (int qt = 0; qt < 2; ++qt)
; #pragma unroll
;     for (int kt = 0; kt < 2; ++kt)
; #pragma unroll
;       for (int r = 0; r < 4; ++r) s[kt][qt][r] = __builtin_amdgcn_exp2f(s[kt][qt][r]);
; template <int DK, int DV, int LDQ, int LDK, int LDV, int LDO, typename TOut, bool PIPE, bool QL, bool VS>
; __device__ __forceinline__ void attn_body16(const bf16_t* Qb, const bf16_t* Kh, const bf16_t* Vh, TOut* Ob, int seq, char* lds) {
;     ...
;       partialSM16(s, m_reg, al, C, THR_S);
;       RESC(al);
;       constexpr int DH = 3; s16x4 pvf[DH + 1][2]; const int vbt = vb0 + vsel * (int)SHM_V;
;       pvh_pro<NVT, VRSB, 0, DH, 0>(vbt, pvf); SBAR();
;       cvt_pa(s, pa, 0); SBAR();
;       pvh_step<NVT, VRSB, 0, DH, true, 0>(o, vbt, pa, pvf, s);
;       pvh_pro<NVT, VRSB, 1, DH, 0>(vbt, pvf); SBAR();
; #pragma unroll
;       for (int qt = 0; qt < 2; ++qt) { float ps = 0.f;
; #pragma unroll
;         for (int kt = 0; kt < 4; ++kt) ps += (s[kt][qt][0] + s[kt][qt][1]) + (s[kt][qt][2] + s[kt][qt][3]);
;         lp[qt] = lp[qt] * al[qt] + ps; }
;       cvt_pa(s, pa, 1); SBAR();
;       pvh_step<NVT, VRSB, 1, DH, false, 0>(o, vbt, pa, pvf, s);
.LBB0_676:
	v_mul_f32_e32 v196, 0xbdd53b94, v176
	v_fmamk_f32 v197, v142, 0x3dd53b94, v196
	v_mul_f32_e32 v142, 0xbdd53b94, v175
	v_fmamk_f32 v122, v122, 0x3dd53b94, v142
	v_fmamk_f32 v123, v123, 0x3dd53b94, v142
	s_mulk_i32 s36, 0x4800
	v_fmamk_f32 v213, v151, 0x3dd53b94, v196
	v_fmamk_f32 v124, v124, 0x3dd53b94, v142
	v_fmamk_f32 v125, v125, 0x3dd53b94, v142
	v_fmamk_f32 v222, v149, 0x3dd53b94, v142
	v_exp_f32_e32 v149, v122
	v_exp_f32_e32 v151, v123
	v_add_u32_e32 v223, s36, v174
	ds_read_b64_tr_b16 v[122:123], v223 offset:0
	v_fmamk_f32 v126, v126, 0x3dd53b94, v196
	v_fmamk_f32 v127, v127, 0x3dd53b94, v196
	v_fmamk_f32 v217, v153, 0x3dd53b94, v196
	v_exp_f32_e32 v153, v124
	v_exp_f32_e32 v183, v125
	ds_read_b64_tr_b16 v[124:125], v223 offset:0x1200
	v_fmamk_f32 v128, v128, 0x3dd53b94, v196
	v_fmamk_f32 v129, v129, 0x3dd53b94, v196
	v_fmamk_f32 v212, v150, 0x3dd53b94, v196
	v_fmamk_f32 v221, v148, 0x3dd53b94, v142
	v_exp_f32_e32 v148, v126
	v_exp_f32_e32 v150, v127
	ds_read_b64_tr_b16 v[126:127], v223 offset:32
	v_fmamk_f32 v215, v152, 0x3dd53b94, v196
	v_fmamk_f32 v130, v130, 0x3dd53b94, v142
	v_fmamk_f32 v131, v131, 0x3dd53b94, v142
	v_exp_f32_e32 v152, v128
	v_exp_f32_e32 v182, v129
	ds_read_b64_tr_b16 v[128:129], v223 offset:0x1220
	v_fmamk_f32 v132, v132, 0x3dd53b94, v142
	v_fmamk_f32 v133, v133, 0x3dd53b94, v142
	v_exp_f32_e32 v185, v130
	v_exp_f32_e32 v199, v131
	ds_read_b64_tr_b16 v[130:131], v223 offset:64
	v_exp_f32_e32 v201, v132
	v_exp_f32_e32 v203, v133
	ds_read_b64_tr_b16 v[132:133], v223 offset:0x1240
	v_fmamk_f32 v134, v134, 0x3dd53b94, v196
	v_fmamk_f32 v135, v135, 0x3dd53b94, v196
	v_fmamk_f32 v136, v136, 0x3dd53b94, v196
	v_fmamk_f32 v137, v137, 0x3dd53b94, v196
	s_add_i32 s29, s29, 1
	v_fmamk_f32 v143, v143, 0x3dd53b94, v196
	v_fmamk_f32 v205, v144, 0x3dd53b94, v196
	v_fmamk_f32 v207, v145, 0x3dd53b94, v196
	v_fmamk_f32 v209, v138, 0x3dd53b94, v142
	v_fmamk_f32 v211, v139, 0x3dd53b94, v142
	v_fmamk_f32 v214, v140, 0x3dd53b94, v142
	v_fmamk_f32 v216, v141, 0x3dd53b94, v142
	v_fmamk_f32 v219, v146, 0x3dd53b94, v142
	v_fmamk_f32 v220, v147, 0x3dd53b94, v142
	v_exp_f32_e32 v184, v134
	v_exp_f32_e32 v198, v135
	v_exp_f32_e32 v200, v136
	v_exp_f32_e32 v202, v137
	v_cvt_pk_bf16_f32 v134, v148, v150
	v_cvt_pk_bf16_f32 v135, v152, v182
	v_cvt_pk_bf16_f32 v136, v184, v198
	v_cvt_pk_bf16_f32 v137, v200, v202
	v_cvt_pk_bf16_f32 v138, v149, v151
	v_cvt_pk_bf16_f32 v139, v153, v183
	v_cvt_pk_bf16_f32 v140, v185, v199
	v_cvt_pk_bf16_f32 v141, v201, v203
	ds_read_b64_tr_b16 v[144:145], v223 offset:0x60
	ds_read_b64_tr_b16 v[146:147], v223 offset:0x1260
	s_waitcnt lgkmcnt(6)
	v_mfma_f32_16x16x32_bf16 v[58:61], v[134:137], v[122:125], v[58:61]
	v_exp_f32_e32 v204, v197
	v_exp_f32_e32 v206, v143
	v_mfma_f32_16x16x32_bf16 v[62:65], v[138:141], v[122:125], v[62:65]
	ds_read_b64_tr_b16 v[122:123], v223 offset:0x80
	ds_read_b64_tr_b16 v[124:125], v223 offset:0x1280
	s_waitcnt lgkmcnt(6)
	v_mfma_f32_16x16x32_bf16 v[50:53], v[134:137], v[126:129], v[50:53]
	v_exp_f32_e32 v208, v205
	v_exp_f32_e32 v210, v207
	v_mfma_f32_16x16x32_bf16 v[54:57], v[138:141], v[126:129], v[54:57]
	ds_read_b64_tr_b16 v[126:127], v223 offset:0xa0
	ds_read_b64_tr_b16 v[128:129], v223 offset:0x12a0
	s_waitcnt lgkmcnt(6)
	v_mfma_f32_16x16x32_bf16 v[42:45], v[134:137], v[130:133], v[42:45]
	v_exp_f32_e32 v205, v209
	v_exp_f32_e32 v207, v211
	v_mfma_f32_16x16x32_bf16 v[46:49], v[138:141], v[130:133], v[46:49]
	ds_read_b64_tr_b16 v[130:131], v223 offset:0xc0
	ds_read_b64_tr_b16 v[132:133], v223 offset:0x12c0
	s_waitcnt lgkmcnt(6)
	v_mfma_f32_16x16x32_bf16 v[34:37], v[134:137], v[144:147], v[34:37]
	v_exp_f32_e32 v209, v214
	v_exp_f32_e32 v211, v216
	v_mfma_f32_16x16x32_bf16 v[38:41], v[138:141], v[144:147], v[38:41]
	ds_read_b64_tr_b16 v[144:145], v223 offset:0xe0
	ds_read_b64_tr_b16 v[146:147], v223 offset:0x12e0
	s_waitcnt lgkmcnt(6)
	v_mfma_f32_16x16x32_bf16 v[26:29], v[134:137], v[122:125], v[26:29]
	v_exp_f32_e32 v212, v212
	v_exp_f32_e32 v214, v213
	v_mfma_f32_16x16x32_bf16 v[30:33], v[138:141], v[122:125], v[30:33]
	s_waitcnt lgkmcnt(4)
	v_mfma_f32_16x16x32_bf16 v[18:21], v[134:137], v[126:129], v[18:21]
	v_exp_f32_e32 v216, v215
	v_exp_f32_e32 v218, v217
	v_mfma_f32_16x16x32_bf16 v[22:25], v[138:141], v[126:129], v[22:25]
	s_waitcnt lgkmcnt(2)
	v_mfma_f32_16x16x32_bf16 v[10:13], v[134:137], v[130:133], v[10:13]
	v_exp_f32_e32 v213, v219
	v_exp_f32_e32 v215, v220
	v_mfma_f32_16x16x32_bf16 v[14:17], v[138:141], v[130:133], v[14:17]
	s_waitcnt lgkmcnt(0)
	v_mfma_f32_16x16x32_bf16 v[2:5], v[134:137], v[144:147], v[2:5]
	v_exp_f32_e32 v217, v221
	v_exp_f32_e32 v219, v222
	v_mfma_f32_16x16x32_bf16 v[6:9], v[138:141], v[144:147], v[6:9]
	ds_read_b64_tr_b16 v[122:123], v223 offset:0x2400
	ds_read_b64_tr_b16 v[124:125], v223 offset:0x3600
	ds_read_b64_tr_b16 v[126:127], v223 offset:0x2420
	ds_read_b64_tr_b16 v[128:129], v223 offset:0x3620
	ds_read_b64_tr_b16 v[130:131], v223 offset:0x2440
	ds_read_b64_tr_b16 v[132:133], v223 offset:0x3640
	v_add_f32_e64 v134, v148, v150
	v_add_f32_e64 v135, v149, v151
	v_pk_add_f32 v[136:137], v[152:153], v[182:183]
	v_pk_add_f32 v[138:139], v[184:185], v[198:199]
	v_pk_add_f32 v[140:141], v[200:201], v[202:203]
	v_pk_add_f32 v[134:135], v[134:135], v[136:137]
	v_pk_add_f32 v[136:137], v[138:139], v[140:141]
	v_pk_add_f32 v[134:135], v[134:135], 0 op_sel_hi:[1,0]
	v_pk_add_f32 v[138:139], v[208:209], v[210:211]
	v_pk_add_f32 v[134:135], v[136:137], v[134:135]
	v_pk_add_f32 v[136:137], v[204:205], v[206:207]
	v_cvt_pk_bf16_f32 v140, v213, v215
	v_pk_add_f32 v[136:137], v[136:137], v[138:139]
	v_pk_add_f32 v[138:139], v[216:217], v[218:219]
	v_pk_add_f32 v[134:135], v[136:137], v[134:135]
	v_pk_add_f32 v[136:137], v[212:213], v[214:215]
	v_cvt_pk_bf16_f32 v141, v217, v219
	v_pk_add_f32 v[136:137], v[136:137], v[138:139]
	v_cvt_pk_bf16_f32 v138, v205, v207
	v_pk_add_f32 v[134:135], v[136:137], v[134:135]
	v_cvt_pk_bf16_f32 v136, v212, v214
	v_pk_fma_f32 v[156:157], v[156:157], v[168:169], v[134:135]
	v_cvt_pk_bf16_f32 v134, v204, v206
	v_cvt_pk_bf16_f32 v135, v208, v210
	v_cvt_pk_bf16_f32 v137, v216, v218
	v_cvt_pk_bf16_f32 v139, v209, v211
	s_mulk_i32 s33, 0x4800
	s_waitcnt vmcnt(0)
; #define SBAR() __builtin_amdgcn_sched_barrier(0)
; #define VWRITE(bv) do { _Pragma("unroll") for (int _q = 0; _q < VP; ++_q) *(bf16x8*)(V_lds + (bv) * SHM_V + VROW(_q) * VRSB + VC8(_q) * 16) = sr_.vs[_q]; } while (0)
; template <int DK, int DV, int LDQ, int LDK, int LDV, int LDO, typename TOut, bool PIPE, bool QL, bool VS>
; __device__ __forceinline__ void attn_body16(const bf16_t* Qb, const bf16_t* Kh, const bf16_t* Vh, TOut* Ob, int seq, char* lds) {
;     ...
;       cvt_pa(s, pa, 1); SBAR();
;       pvh_step<NVT, VRSB, 1, DH, false, 0>(o, vbt, pa, pvf, s);
;       if constexpr (VS) {
;         asm volatile("s_waitcnt vmcnt(0)" ::: "memory");
;         __syncthreads();
;         if (j + 1 < NT) VWRITE(0);
;       } else if (j + 1 < NT) { asm volatile("s_waitcnt vmcnt(0)" ::: "memory"); VWRITE(bsel ^ 1); }
;       __syncthreads();
	v_add3_u32 v159, s33, v187, v177
	v_add3_u32 v161, s33, v188, v186
	ds_write_b128 v159, v[118:121]
	ds_write_b128 v161, v[114:117]
	ds_read_b64_tr_b16 v[144:145], v223 offset:0x2460
	ds_read_b64_tr_b16 v[146:147], v223 offset:0x3660
	s_waitcnt lgkmcnt(6)
	s_nop 0
	v_mfma_f32_16x16x32_bf16 v[58:61], v[134:137], v[122:125], v[58:61]
	v_mfma_f32_16x16x32_bf16 v[62:65], v[138:141], v[122:125], v[62:65]
	ds_read_b64_tr_b16 v[122:123], v223 offset:0x2480
	ds_read_b64_tr_b16 v[124:125], v223 offset:0x3680
	s_waitcnt lgkmcnt(6)
	v_mfma_f32_16x16x32_bf16 v[50:53], v[134:137], v[126:129], v[50:53]
	v_mfma_f32_16x16x32_bf16 v[54:57], v[138:141], v[126:129], v[54:57]
	ds_read_b64_tr_b16 v[126:127], v223 offset:0x24a0
	ds_read_b64_tr_b16 v[128:129], v223 offset:0x36a0
	s_waitcnt lgkmcnt(6)
	v_mfma_f32_16x16x32_bf16 v[42:45], v[134:137], v[130:133], v[42:45]
	v_mfma_f32_16x16x32_bf16 v[46:49], v[138:141], v[130:133], v[46:49]
	ds_read_b64_tr_b16 v[130:131], v223 offset:0x24c0
	ds_read_b64_tr_b16 v[132:133], v223 offset:0x36c0
	s_waitcnt lgkmcnt(6)
	v_mfma_f32_16x16x32_bf16 v[34:37], v[134:137], v[144:147], v[34:37]
	v_mfma_f32_16x16x32_bf16 v[38:41], v[138:141], v[144:147], v[38:41]
	ds_read_b64_tr_b16 v[144:145], v223 offset:0x24e0
	ds_read_b64_tr_b16 v[146:147], v223 offset:0x36e0
	s_waitcnt lgkmcnt(6)
	v_mfma_f32_16x16x32_bf16 v[26:29], v[134:137], v[122:125], v[26:29]
	v_mfma_f32_16x16x32_bf16 v[30:33], v[138:141], v[122:125], v[30:33]
	s_waitcnt lgkmcnt(4)
	v_mfma_f32_16x16x32_bf16 v[18:21], v[134:137], v[126:129], v[18:21]
	v_mfma_f32_16x16x32_bf16 v[22:25], v[138:141], v[126:129], v[22:25]
	s_waitcnt lgkmcnt(2)
	v_mfma_f32_16x16x32_bf16 v[10:13], v[134:137], v[130:133], v[10:13]
	v_mfma_f32_16x16x32_bf16 v[14:17], v[138:141], v[130:133], v[14:17]
	s_waitcnt lgkmcnt(0)
	v_mfma_f32_16x16x32_bf16 v[2:5], v[134:137], v[144:147], v[2:5]
	v_mfma_f32_16x16x32_bf16 v[6:9], v[138:141], v[144:147], v[6:9]
	s_waitcnt vmcnt(0)
	s_add_u32 s52, s52, s80
	s_addc_u32 s53, s53, s81
	s_add_u32 s54, s54, s96
	s_addc_u32 s55, s55, s97
	s_cmp_eq_u32 s30, s29
	s_waitcnt lgkmcnt(0)
	s_barrier
	s_cbranch_scc1 .LBB0_683
; #define SBAR() __builtin_amdgcn_sched_barrier(0)
; template <int N> __device__ __forceinline__ void lgkm_wait() { asm volatile("s_waitcnt lgkmcnt(%0)" :: "i"(N) : "memory"); }
; template <int DK, int D, int I> __device__ __forceinline__ void qk_step(f32x4 (&s)[4][2], bf16x8 (&fr)[D + 1], const int (&ka)[DK / 32], const bf16x8 (&qr)[2][DK / 32]) {
;   constexpr int KS = DK / 32, N = 4 * KS;
;   if constexpr (I < N) {
;     if constexpr (I + D < N) qk_ld<DK, D, I + D>(fr, ka);
;     lgkm_wait<((N - 1 - I) < D ? (N - 1 - I) : D)>(); SBAR();
;     constexpr int kt = I / KS, ks = I % KS;
;     if constexpr (ks == 0) { s[kt][0] = __builtin_amdgcn_mfma_f32_16x16x32_bf16(fr[I % (D + 1)], qr[0][ks], (f32x4){0.f, 0.f, 0.f, 0.f}, 0, 0, 0); s[kt][1] = __builtin_amdgcn_mfma_f32_16x16x32_bf16(fr[I % (D + 1)], qr[1][ks], (f32x4){0.f, 0.f, 0.f, 0.f}, 0, 0, 0); }
;     else { s[kt][0] = __builtin_amdgcn_mfma_f32_16x16x32_bf16(fr[I % (D + 1)], qr[0][ks], s[kt][0], 0, 0, 0); s[kt][1] = __builtin_amdgcn_mfma_f32_16x16x32_bf16(fr[I % (D + 1)], qr[1][ks], s[kt][1], 0, 0, 0); }
;     SBAR();
;     qk_step<DK, D, I + 1>(s, fr, ka, qr);
;   }
; }
; template <int DK, int D, int I> __device__ __forceinline__ void qk_pro(bf16x8 (&fr)[D + 1], const int (&ka)[DK / 32]) { if constexpr (I < D) { qk_ld<DK, D, I>(fr, ka); qk_pro<DK, D, I + 1>(fr, ka); } }
; template <int DK>
; __device__ __forceinline__ void qkt16(f32x4 (&s)[4][2], const char* Ks, const bf16x8 (&qr)[2][DK / 32], int c, int g) {
;   constexpr int D = 4; int ka[DK / 32]; bf16x8 fr[D + 1];
;   const int kb = (int)(uintptr_t)Ks + c * (DK * 2);
; #pragma unroll
;   for (int ks = 0; ks < DK / 32; ++ks) ka[ks] = kb + (((ks * 32 + g * 8) * 2) ^ ((c & 7) << 4));
;   qk_pro<DK, D, 0>(fr, ka); qk_step<DK, D, 0>(s, fr, ka, qr);
; }
; __device__ __forceinline__ void partialSM16(f32x4 (&s)[4][2], float (&m_reg)[2], float (&alpha)[2], const float C, const float thr_s) {
;   float pmax[2];
; #pragma unroll
;   for (int qt = 0; qt < 2; ++qt) { float v = s[0][qt][0];
; #pragma unroll
;     for (int kt = 0; kt < 4; ++kt)
; #pragma unroll
;       for (int r = 0; r < 4; ++r) v = fmaxf(v, s[kt][qt][r]);
;     pmax[qt] = xmax4(v); }
;   float mn[2];
;   if (__builtin_expect(__all(pmax[0] - m_reg[0] <= thr_s && pmax[1] - m_reg[1] <= thr_s), 1)) { mn[0] = m_reg[0]; mn[1] = m_reg[1]; alpha[0] = 1.f; alpha[1] = 1.f; }
.LBB0_677:
	s_and_b32 s36, s29, 1
	s_xor_b32 s33, s36, 1
	s_mul_i32 s6, s33, 0x6000
	s_add_i32 s6, s6, s28
	s_mov_b32 m0, s6
	global_load_dwordx4 v[118:121], v164, s[54:55]
	s_nop 0
	global_load_dwordx4 v[114:117], v166, s[54:55]
	s_nop 0
	global_load_lds_dwordx4 v158, s[52:53]
	s_add_i32 m0, s6, 0x2000
	s_nop 0
	global_load_lds_dwordx4 v160, s[52:53]
	s_add_i32 m0, s6, 0x4000
	s_nop 0
	global_load_lds_dwordx4 v162, s[52:53]
	s_cmp_lg_u32 s27, -1
	s_mul_i32 s6, s36, 0x6000
	s_cselect_b32 s7, s27, 0
	s_add_i32 s7, s7, s6
	v_add_u32_e32 v122, s7, v189
	v_add_u32_e32 v168, v122, v190
	v_add_u32_e32 v169, v122, v191
	ds_read_b128 v[122:125], v168 offset:0
	ds_read_b128 v[126:129], v169 offset:0
	ds_read_b128 v[130:133], v168 offset:0x80
	ds_read_b128 v[134:137], v169 offset:0x80
	ds_read_b128 v[138:141], v168 offset:0x100
	s_waitcnt lgkmcnt(4)
	s_nop 0
	v_mfma_f32_16x16x32_bf16 v[142:145], v[122:125], v[102:105], 0
	v_mfma_f32_16x16x32_bf16 v[122:125], v[122:125], v[110:113], 0
	ds_read_b128 v[146:149], v169 offset:0x100
	s_waitcnt lgkmcnt(4)
	v_mfma_f32_16x16x32_bf16 v[142:145], v[126:129], v[94:97], v[142:145]
	v_mfma_f32_16x16x32_bf16 v[122:125], v[126:129], v[106:109], v[122:125]
	ds_read_b128 v[150:153], v168 offset:0x1800
	s_waitcnt lgkmcnt(4)
	v_mfma_f32_16x16x32_bf16 v[126:129], v[130:133], v[86:89], v[142:145]
	v_mfma_f32_16x16x32_bf16 v[122:125], v[130:133], v[98:101], v[122:125]
	ds_read_b128 v[130:133], v169 offset:0x1800
	s_waitcnt lgkmcnt(4)
	v_mfma_f32_16x16x32_bf16 v[126:129], v[134:137], v[78:81], v[126:129]
	v_mfma_f32_16x16x32_bf16 v[122:125], v[134:137], v[90:93], v[122:125]
	ds_read_b128 v[134:137], v168 offset:0x1880
	s_waitcnt lgkmcnt(4)
	v_mfma_f32_16x16x32_bf16 v[126:129], v[138:141], v[70:73], v[126:129]
	v_mfma_f32_16x16x32_bf16 v[122:125], v[138:141], v[82:85], v[122:125]
	ds_read_b128 v[138:141], v169 offset:0x1880
	s_waitcnt lgkmcnt(4)
	v_mfma_f32_16x16x32_bf16 v[126:129], v[146:149], v[66:69], v[126:129]
	v_mfma_f32_16x16x32_bf16 v[122:125], v[146:149], v[74:77], v[122:125]
	ds_read_b128 v[142:145], v168 offset:0x1900
	s_waitcnt lgkmcnt(4)
	v_mfma_f32_16x16x32_bf16 v[146:149], v[150:153], v[102:105], 0
	v_mfma_f32_16x16x32_bf16 v[150:153], v[150:153], v[110:113], 0
	ds_read_b128 v[196:199], v169 offset:0x1900
	s_waitcnt lgkmcnt(4)
	v_mfma_f32_16x16x32_bf16 v[146:149], v[130:133], v[94:97], v[146:149]
	v_mfma_f32_16x16x32_bf16 v[130:133], v[130:133], v[106:109], v[150:153]
	ds_read_b128 v[150:153], v168 offset:0x3000
	s_waitcnt lgkmcnt(4)
	v_mfma_f32_16x16x32_bf16 v[146:149], v[134:137], v[86:89], v[146:149]
	v_mfma_f32_16x16x32_bf16 v[130:133], v[134:137], v[98:101], v[130:133]
	ds_read_b128 v[200:203], v169 offset:0x3000
	s_waitcnt lgkmcnt(4)
	v_mfma_f32_16x16x32_bf16 v[134:137], v[138:141], v[78:81], v[146:149]
	v_mfma_f32_16x16x32_bf16 v[130:133], v[138:141], v[90:93], v[130:133]
	ds_read_b128 v[138:141], v168 offset:0x3080
	s_waitcnt lgkmcnt(4)
	v_mfma_f32_16x16x32_bf16 v[134:137], v[142:145], v[70:73], v[134:137]
	v_mfma_f32_16x16x32_bf16 v[130:133], v[142:145], v[82:85], v[130:133]
	ds_read_b128 v[142:145], v169 offset:0x3080
	s_waitcnt lgkmcnt(4)
	v_mfma_f32_16x16x32_bf16 v[134:137], v[196:199], v[66:69], v[134:137]
	v_mfma_f32_16x16x32_bf16 v[130:133], v[196:199], v[74:77], v[130:133]
	ds_read_b128 v[146:149], v168 offset:0x3100
	s_waitcnt lgkmcnt(4)
	v_mfma_f32_16x16x32_bf16 v[196:199], v[150:153], v[102:105], 0
	v_mfma_f32_16x16x32_bf16 v[150:153], v[150:153], v[110:113], 0
	ds_read_b128 v[204:207], v169 offset:0x3100
	s_waitcnt lgkmcnt(4)
	v_mfma_f32_16x16x32_bf16 v[196:199], v[200:203], v[94:97], v[196:199]
	v_mfma_f32_16x16x32_bf16 v[150:153], v[200:203], v[106:109], v[150:153]
	ds_read_b128 v[200:203], v168 offset:0x4800
	s_waitcnt lgkmcnt(4)
	v_mfma_f32_16x16x32_bf16 v[196:199], v[138:141], v[86:89], v[196:199]
	v_mfma_f32_16x16x32_bf16 v[138:141], v[138:141], v[98:101], v[150:153]
	ds_read_b128 v[150:153], v169 offset:0x4800
	s_waitcnt lgkmcnt(4)
	v_mfma_f32_16x16x32_bf16 v[196:199], v[142:145], v[78:81], v[196:199]
	v_mfma_f32_16x16x32_bf16 v[138:141], v[142:145], v[90:93], v[138:141]
	ds_read_b128 v[208:211], v168 offset:0x4880
	s_waitcnt lgkmcnt(4)
	v_mfma_f32_16x16x32_bf16 v[142:145], v[146:149], v[70:73], v[196:199]
	v_mfma_f32_16x16x32_bf16 v[138:141], v[146:149], v[82:85], v[138:141]
	ds_read_b128 v[146:149], v169 offset:0x4880
	s_waitcnt lgkmcnt(4)
	v_mfma_f32_16x16x32_bf16 v[142:145], v[204:207], v[66:69], v[142:145]
	v_mfma_f32_16x16x32_bf16 v[138:141], v[204:207], v[74:77], v[138:141]
	ds_read_b128 v[196:199], v168 offset:0x4900
	s_waitcnt lgkmcnt(4)
	v_mfma_f32_16x16x32_bf16 v[204:207], v[200:203], v[102:105], 0
	v_mfma_f32_16x16x32_bf16 v[200:203], v[200:203], v[110:113], 0
	ds_read_b128 v[212:215], v169 offset:0x4900
	s_waitcnt lgkmcnt(4)
	v_mfma_f32_16x16x32_bf16 v[204:207], v[150:153], v[94:97], v[204:207]
	v_mfma_f32_16x16x32_bf16 v[150:153], v[150:153], v[106:109], v[200:203]
	s_waitcnt lgkmcnt(3)
	v_mfma_f32_16x16x32_bf16 v[150:153], v[208:211], v[98:101], v[150:153]
	v_mfma_f32_16x16x32_bf16 v[200:203], v[208:211], v[86:89], v[204:207]
	s_waitcnt lgkmcnt(2)
	v_mfma_f32_16x16x32_bf16 v[200:203], v[146:149], v[78:81], v[200:203]
	v_mfma_f32_16x16x32_bf16 v[146:149], v[146:149], v[90:93], v[150:153]
	s_waitcnt lgkmcnt(1)
	v_mfma_f32_16x16x32_bf16 v[150:153], v[196:199], v[70:73], v[200:203]
	v_mfma_f32_16x16x32_bf16 v[146:149], v[196:199], v[82:85], v[146:149]
	s_waitcnt lgkmcnt(0)
	v_mfma_f32_16x16x32_bf16 v[150:153], v[212:215], v[66:69], v[150:153]
	v_mfma_f32_16x16x32_bf16 v[146:149], v[212:215], v[74:77], v[146:149]
	s_nop 1
	v_max_f32_e32 v168, v126, v127
	v_max3_f32 v168, v168, v128, v129
	v_max3_f32 v168, v168, v134, v135
	v_max3_f32 v168, v168, v136, v137
	v_max3_f32 v168, v168, v142, v143
	v_max3_f32 v168, v168, v144, v145
	v_max3_f32 v168, v168, v150, v151
	v_max3_f32 v168, v168, v152, v153
	v_mov_b32_e32 v169, v168
	s_nop 1
	v_permlane16_swap_b32_e32 v168, v169
	v_max_f32_e32 v168, v168, v169
	v_mov_b32_e32 v169, v168
	s_nop 1
	v_permlane32_swap_b32_e32 v168, v169
	v_max_f32_e32 v169, v168, v169
	s_nop 1
	v_max_f32_e32 v168, v122, v123
	v_max3_f32 v168, v168, v124, v125
	v_max3_f32 v168, v168, v130, v131
	v_max3_f32 v168, v168, v132, v133
	v_max3_f32 v168, v168, v138, v139
	v_max3_f32 v168, v168, v140, v141
	v_max3_f32 v168, v168, v146, v147
	v_max3_f32 v168, v168, v148, v149
	v_mov_b32_e32 v182, v168
	s_nop 1
	v_permlane16_swap_b32_e32 v168, v182
	v_max_f32_e32 v168, v168, v182
	v_mov_b32_e32 v182, v168
	s_nop 1
	v_permlane32_swap_b32_e32 v168, v182
	v_max_f32_e32 v196, v168, v182
	v_sub_f32_e32 v168, v169, v176
	v_cmp_ge_f32_e32 vcc, s49, v168
	v_sub_f32_e32 v168, v196, v175
	v_cmp_ge_f32_e64 s[6:7], s49, v168
	s_and_b64 s[6:7], vcc, s[6:7]
	s_cmp_eq_u64 s[6:7], exec
	v_mov_b32_e32 v168, 1.0
	s_cbranch_scc0 .LBB0_682
	v_mov_b32_e32 v169, 1.0
